# adds mLSTM seq-loop: P3 MFMA-operand LDS reads and P2 C-update chunk 2/3 LDS reads hoisted (issued up front into spare VGPRs)
# speedup vs baseline: 1.0028x; 1.0028x over previous
; #define LAS __attribute__((address_space(3)))
; __device__ __forceinline__ bf16_t f2bf(float f) { return (bf16_t)(pk2(f, 0.f) & 0xffffu); }
; __device__ __forceinline__ float fast_rcp(float x) { return __builtin_amdgcn_rcpf(x); }
; #define MFMA32(a, b, c) __builtin_amdgcn_mfma_f32_32x32x16_bf16((a), (b), (c), 0, 0, 0)
; __device__ __forceinline__ void mlstm_unit(const Params& p, int l, int b, int h, LAS unsigned char* lds) {
;     ...
;         {
;             const int tblk = w4 & 1, vblk = w4 >> 1;
;             f32x16 a1, a2;
; #pragma unroll
;             for (int i = 0; i < 16; ++i) { a1[i] = 0.f; a2[i] = 0.f; }
; #pragma unroll
;             for (int c = 0; c < 4; ++c) { const bf16x8 bv = lds_rd16(L + ML_VT + (32 * vblk + r32) * 144 + hi * 16 + c * 32), as = lds_rd16(L + ML_SW + (32 * tblk + r32) * 144 + hi * 16 + c * 32);
;                 const bf16x8 aq = lds_rd16(L + ML_QS + (32 * tblk + r32) * 144 + hi * 16 + c * 32), bc2 = lds_rd16(CTc + (32 * vblk + r32) * 144 + hi * 16 + c * 32);
;                 a1 = MFMA32(as, bv, a1); a2 = MFMA32(aq, bc2, a2); }
;             const int tau0 = cidx * 64; const size_t rowc = tau0 < CTX ? (size_t)(ctxrow0 + tau0) : (size_t)(latrow0 + tau0 - CTX);
;             bf16_t* hp = HX + rowc * 256 + h * 64 + 32 * vblk + r32;
; #pragma unroll
;             for (int ig = 0; ig < 4; ++ig) { const int t0 = 32 * tblk + 8 * ig + 4 * hi;
;                 const f32x4 d0 = *(const LAS f32x4*)(L + ML_TAB + T_DP0 + t0 * 4), d1 = *(const LAS f32x4*)(L + ML_TAB + T_DP1 + t0 * 4), di = *(const LAS f32x4*)(L + ML_TAB + T_DI + t0 * 4),
;                             w4v = *(const LAS f32x4*)(L + ML_TAB + T_WP + t0 * 4), em = *(const LAS f32x4*)(L + ML_TAB + T_EMT + t0 * 4);
; #pragma unroll
;                 for (int e = 0; e < 4; ++e) { const float den = d0[e] + d1[e] + w4v[e] * di[e]; const float dn = fmaxf(fabsf(den), em[e]);
;                     const float hv = (a1[4 * ig + e] + w4v[e] * a2[4 * ig + e]) * fast_rcp(dn); hp[(size_t)(t0 + e) * 256] = f2bf(hv); } }
;         }
.LBB0_456:
	s_and_b64 s[76:77], s[76:77], exec
	s_waitcnt lgkmcnt(0)
	s_barrier
	s_cselect_b32 s78, s88, 0xd800
	ds_read_b128 v[16:19], v135 offset:36864
	ds_read_b128 v[20:23], v116 offset:27648
	ds_read_b128 v[106:109], v116 offset:27680
	v_add_f32_e32 v136, v32, v33
	v_add_u32_e32 v85, s78, v116
	ds_read_b128 v[32:35], v135
	ds_read_b128 v[138:141], v135 offset:32
	ds_read_b128 v[36:39], v85
	ds_read_b128 v[142:145], v85 offset:32
	ds_read_b128 v[146:149], v135 offset:36896
	s_waitcnt lgkmcnt(6)
	v_mfma_f32_32x32x16_bf16 v[16:31], v[16:19], v[20:23], 0
	ds_read_b128 v[162:165], v116 offset:27712
	ds_read_b128 v[166:169], v135 offset:36928
	ds_read_b128 v[170:173], v135 offset:64
	ds_read_b128 v[174:177], v85 offset:64
	ds_read_b128 v[178:181], v116 offset:27744
	ds_read_b128 v[182:185], v135 offset:36960
	ds_read_b128 v[186:189], v135 offset:96
	ds_read_b128 v[190:193], v85 offset:96
	s_cmp_gt_u32 s90, 3
	s_cselect_b32 s64, 0x47, 3
	s_add_i32 s64, s64, s47
	s_addk_i32 s64, 0xffba
	s_and_b64 s[76:77], s[4:5], exec
	s_cselect_b32 s64, s90, s64
	s_lshl_b32 s76, s64, 6
	s_waitcnt lgkmcnt(10)
	v_mfma_f32_32x32x16_bf16 v[32:47], v[32:35], v[36:39], 0
	s_add_i32 s78, s76, s66
	s_ashr_i32 s77, s78, 31
	s_add_i32 s76, s76, s84
	s_cmp_lt_i32 s64, 4
	s_cselect_b32 s77, s77, 0
	s_cselect_b32 s76, s78, s76
	s_lshl_b64 s[76:77], s[76:77], 9
	s_waitcnt lgkmcnt(8)
	v_mfma_f32_32x32x16_bf16 v[16:31], v[146:149], v[106:109], v[16:31]
	s_movk_i32 s64, 0x1000
	s_xor_b32 s44, s44, 1
	s_add_i32 s47, s47, -1
	s_cmp_eq_u32 s47, 2
	s_mov_b32 s90, s92
	v_mfma_f32_32x32x16_bf16 v[32:47], v[138:141], v[142:145], v[32:47]
	s_waitcnt lgkmcnt(6)
	v_mfma_f32_32x32x16_bf16 v[16:31], v[166:169], v[162:165], v[16:31]
	s_waitcnt lgkmcnt(4)
	v_mfma_f32_32x32x16_bf16 v[32:47], v[170:173], v[174:177], v[32:47]
	v_add_u32_e32 v85, s46, v122
	s_waitcnt lgkmcnt(2)
	v_mfma_f32_32x32x16_bf16 v[16:31], v[182:185], v[178:181], v[16:31]
	ds_read_b128 v[138:141], v85
	v_add_u32_e32 v85, s2, v122
	v_add_u32_e32 v108, s33, v122
	v_lshl_add_u64 v[106:107], v[98:99], 0, s[76:77]
	s_waitcnt lgkmcnt(1)
	v_mfma_f32_32x32x16_bf16 v[32:47], v[186:189], v[190:193], v[32:47]
	ds_read_b128 v[142:145], v85
	v_add_u32_e32 v85, s67, v122
	ds_read_b128 v[146:149], v85
	ds_read_b128 v[84:87], v84 offset:65024
	ds_read_b128 v[150:153], v108
	s_waitcnt lgkmcnt(3)
	v_add_f32_e32 v108, v138, v142
	s_waitcnt lgkmcnt(1)
	v_fmac_f32_e32 v108, v146, v84
	s_waitcnt lgkmcnt(0)
	v_max_f32_e32 v109, v150, v150
	v_max_f32_e64 v108, |v108|, v109
	v_fma_f32 v16, v32, v84, v16
	v_rcp_f32_e32 v32, v108
	v_lshl_add_u64 v[108:109], v[106:107], 0, v[160:161]
	v_fma_f32 v17, v33, v85, v17
	v_add_u32_e32 v84, s67, v123
	v_mul_f32_e32 v16, v16, v32
	v_cvt_pk_bf16_f32 v16, v16, s0
	global_store_short v[108:109], v16, off
	v_add_f32_e32 v16, v139, v143
	v_fmac_f32_e32 v16, v147, v85
	v_max_f32_e32 v32, v151, v151
	v_max_f32_e64 v16, |v16|, v32
	v_rcp_f32_e32 v16, v16
	v_add_u32_e32 v32, s2, v123
	v_mul_f32_e32 v16, v17, v16
	v_cvt_pk_bf16_f32 v16, v16, s0
	global_store_short v[108:109], v16, off offset:512
	v_add_f32_e32 v16, v140, v144
	v_fmac_f32_e32 v16, v148, v86
	v_max_f32_e32 v17, v152, v152
	v_max_f32_e64 v16, |v16|, v17
	v_rcp_f32_e32 v16, v16
	v_fma_f32 v17, v34, v86, v18
	v_mul_f32_e32 v16, v17, v16
	v_cvt_pk_bf16_f32 v16, v16, s0
	global_store_short v[108:109], v16, off offset:1024
	v_add_f32_e32 v16, v141, v145
	v_fmac_f32_e32 v16, v149, v87
	v_max_f32_e32 v17, v153, v153
	v_max_f32_e64 v16, |v16|, v17
	v_rcp_f32_e32 v16, v16
	v_fma_f32 v17, v35, v87, v19
	ds_read_b128 v[32:35], v32
	v_mul_f32_e32 v16, v17, v16
	v_cvt_pk_bf16_f32 v16, v16, s0
	global_store_short v[108:109], v16, off offset:1536
	v_add_u32_e32 v16, s46, v123
	ds_read_b128 v[16:19], v16
	ds_read_b128 v[84:87], v84
	ds_read_b128 v[138:141], v103 offset:65024
	v_add_u32_e32 v103, s33, v123
	ds_read_b128 v[142:145], v103
	v_mov_b32_e32 v103, v161
	s_waitcnt lgkmcnt(3)
	v_add_f32_e32 v16, v16, v32
	s_waitcnt lgkmcnt(1)
	v_fmac_f32_e32 v16, v84, v138
	v_fma_f32 v20, v36, v138, v20
	s_waitcnt lgkmcnt(0)
; #define LAS __attribute__((address_space(3)))
; __device__ __forceinline__ bf16_t f2bf(float f) { return (bf16_t)(pk2(f, 0.f) & 0xffffu); }
; __device__ __forceinline__ float fast_rcp(float x) { return __builtin_amdgcn_rcpf(x); }
; #define ML_BAR() asm volatile("s_waitcnt lgkmcnt(0)\n\ts_barrier" ::: "memory")
; __device__ __forceinline__ void mlstm_unit(const Params& p, int l, int b, int h, LAS unsigned char* lds) {
;     ...
;             const int tau0 = cidx * 64; const size_t rowc = tau0 < CTX ? (size_t)(ctxrow0 + tau0) : (size_t)(latrow0 + tau0 - CTX);
;             bf16_t* hp = HX + rowc * 256 + h * 64 + 32 * vblk + r32;
; #pragma unroll
;             for (int ig = 0; ig < 4; ++ig) { const int t0 = 32 * tblk + 8 * ig + 4 * hi;
;                 const f32x4 d0 = *(const LAS f32x4*)(L + ML_TAB + T_DP0 + t0 * 4), d1 = *(const LAS f32x4*)(L + ML_TAB + T_DP1 + t0 * 4), di = *(const LAS f32x4*)(L + ML_TAB + T_DI + t0 * 4),
;                             w4v = *(const LAS f32x4*)(L + ML_TAB + T_WP + t0 * 4), em = *(const LAS f32x4*)(L + ML_TAB + T_EMT + t0 * 4);
; #pragma unroll
;                 for (int e = 0; e < 4; ++e) { const float den = d0[e] + d1[e] + w4v[e] * di[e]; const float dn = fmaxf(fabsf(den), em[e]);
;                     const float hv = (a1[4 * ig + e] + w4v[e] * a2[4 * ig + e]) * fast_rcp(dn); hp[(size_t)(t0 + e) * 256] = f2bf(hv); } }
;         }
;         mstate = mnext; cur ^= 1;
;         ML_BAR();
	v_max_f32_e32 v32, v142, v142
	v_max_f32_e64 v16, |v16|, v32
	v_rcp_f32_e32 v16, v16
	v_lshl_add_u64 v[146:147], v[106:107], 0, v[102:103]
	v_add_f32_e32 v18, v18, v34
	v_fmac_f32_e32 v18, v86, v140
	v_mul_f32_e32 v16, v20, v16
	v_cvt_pk_bf16_f32 v16, v16, s0
	global_store_short v[146:147], v16, off
	v_add_f32_e32 v16, v17, v33
	v_fmac_f32_e32 v16, v85, v139
	v_max_f32_e32 v17, v143, v143
	v_max_f32_e64 v16, |v16|, v17
	v_rcp_f32_e32 v16, v16
	v_fma_f32 v17, v37, v139, v21
	v_add_u32_e32 v32, s67, v124
	v_add_u32_e32 v84, s33, v124
	v_mul_f32_e32 v16, v17, v16
	v_cvt_pk_bf16_f32 v20, v16, s0
	v_add_co_u32_e32 v16, vcc, s64, v108
	s_movk_i32 s64, 0x2000
	s_nop 0
	v_addc_co_u32_e32 v17, vcc, 0, v109, vcc
	global_store_short v[16:17], v20, off offset:512
	v_max_f32_e32 v20, v144, v144
	v_max_f32_e64 v18, |v18|, v20
	v_rcp_f32_e32 v18, v18
	v_fma_f32 v20, v38, v140, v22
	v_mul_f32_e32 v18, v20, v18
	v_cvt_pk_bf16_f32 v18, v18, s0
	global_store_short v[16:17], v18, off offset:1024
	v_add_f32_e32 v18, v19, v35
	v_fmac_f32_e32 v18, v87, v141
	v_max_f32_e32 v19, v145, v145
	v_max_f32_e64 v18, |v18|, v19
	v_rcp_f32_e32 v18, v18
	v_fma_f32 v19, v39, v141, v23
	v_add_u32_e32 v20, s2, v124
	ds_read_b128 v[20:23], v20
	v_mul_f32_e32 v18, v19, v18
	v_cvt_pk_bf16_f32 v18, v18, s0
	global_store_short v[16:17], v18, off offset:1536
	v_add_u32_e32 v16, s46, v124
	ds_read_b128 v[16:19], v16
	ds_read_b128 v[32:35], v32
	ds_read_b128 v[36:39], v105 offset:65024
	ds_read_b128 v[84:87], v84
	v_mov_b32_e32 v105, v161
	v_lshl_add_u64 v[138:139], v[106:107], 0, v[104:105]
	s_waitcnt lgkmcnt(3)
	v_add_f32_e32 v16, v16, v20
	s_waitcnt lgkmcnt(1)
	v_fmac_f32_e32 v16, v32, v36
	s_waitcnt lgkmcnt(0)
	v_max_f32_e32 v20, v84, v84
	v_max_f32_e64 v16, |v16|, v20
	v_rcp_f32_e32 v16, v16
	v_fma_f32 v20, v40, v36, v24
	v_add_f32_e32 v18, v18, v22
	v_fmac_f32_e32 v18, v34, v38
	v_mul_f32_e32 v16, v20, v16
	v_cvt_pk_bf16_f32 v16, v16, s0
	global_store_short v[138:139], v16, off
	v_add_f32_e32 v16, v17, v21
	v_fmac_f32_e32 v16, v33, v37
	v_max_f32_e32 v17, v85, v85
	v_max_f32_e64 v16, |v16|, v17
	v_rcp_f32_e32 v16, v16
	v_fma_f32 v17, v41, v37, v25
	v_add_u32_e32 v24, s67, v125
	v_add_u32_e32 v36, s33, v125
	v_mul_f32_e32 v16, v17, v16
	v_cvt_pk_bf16_f32 v20, v16, s0
	v_add_co_u32_e32 v16, vcc, s64, v108
	v_lshl_add_u64 v[40:41], v[100:101], 1, v[106:107]
	s_nop 0
	v_addc_co_u32_e32 v17, vcc, 0, v109, vcc
	global_store_short v[16:17], v20, off offset:512
	v_max_f32_e32 v20, v86, v86
	v_max_f32_e64 v18, |v18|, v20
	v_rcp_f32_e32 v18, v18
	v_fma_f32 v20, v42, v38, v26
	s_movk_i32 s64, 0x3000
	v_mul_f32_e32 v18, v20, v18
	v_cvt_pk_bf16_f32 v18, v18, s0
	global_store_short v[16:17], v18, off offset:1024
	v_add_f32_e32 v18, v19, v23
	v_fmac_f32_e32 v18, v35, v39
	v_max_f32_e32 v19, v87, v87
	v_max_f32_e64 v18, |v18|, v19
	v_rcp_f32_e32 v18, v18
	v_fma_f32 v19, v43, v39, v27
	v_add_u32_e32 v20, s2, v125
	ds_read_b128 v[20:23], v20
	v_mul_f32_e32 v18, v19, v18
	v_cvt_pk_bf16_f32 v18, v18, s0
	global_store_short v[16:17], v18, off offset:1536
	v_add_u32_e32 v16, s46, v125
	ds_read_b128 v[16:19], v16
	ds_read_b128 v[24:27], v24
	ds_read_b128 v[32:35], v83 offset:65024
	ds_read_b128 v[36:39], v36
	s_waitcnt lgkmcnt(3)
	v_add_f32_e32 v16, v16, v20
	s_waitcnt lgkmcnt(1)
	v_fmac_f32_e32 v16, v24, v32
	s_waitcnt lgkmcnt(0)
	v_max_f32_e32 v20, v36, v36
	v_max_f32_e64 v16, |v16|, v20
	v_rcp_f32_e32 v16, v16
	v_fma_f32 v20, v44, v32, v28
	v_add_f32_e32 v18, v18, v22
	v_fmac_f32_e32 v18, v26, v34
	v_mul_f32_e32 v16, v20, v16
	v_cvt_pk_bf16_f32 v16, v16, s0
	global_store_short v[40:41], v16, off
	v_add_f32_e32 v16, v17, v21
	v_fmac_f32_e32 v16, v25, v33
	v_max_f32_e32 v17, v37, v37
	v_max_f32_e64 v16, |v16|, v17
	v_rcp_f32_e32 v16, v16
	v_fma_f32 v17, v45, v33, v29
	v_fmac_f32_e32 v31, v47, v35
	v_mul_f32_e32 v16, v17, v16
	v_cvt_pk_bf16_f32 v20, v16, s0
	v_add_co_u32_e32 v16, vcc, s64, v108
	s_nop 1
	v_addc_co_u32_e32 v17, vcc, 0, v109, vcc
	global_store_short v[16:17], v20, off offset:512
	v_max_f32_e32 v20, v38, v38
	v_max_f32_e64 v18, |v18|, v20
	v_rcp_f32_e32 v18, v18
	v_fma_f32 v20, v46, v34, v30
	v_mul_f32_e32 v18, v20, v18
	v_cvt_pk_bf16_f32 v18, v18, s0
	global_store_short v[16:17], v18, off offset:1024
	v_add_f32_e32 v18, v19, v23
	v_fmac_f32_e32 v18, v27, v35
	v_max_f32_e32 v19, v39, v39
	v_max_f32_e64 v18, |v18|, v19
	v_rcp_f32_e32 v18, v18
	s_nop 0
	v_mul_f32_e32 v18, v31, v18
	v_cvt_pk_bf16_f32 v18, v18, s0
	global_store_short v[16:17], v18, off offset:1536
	s_waitcnt lgkmcnt(0)
	s_barrier
	s_cbranch_scc1 .LBB0_472

; #define LAS __attribute__((address_space(3)))
; __device__ __forceinline__ unsigned pk2(float lo, float hi) { f32x2_t v = {lo, hi}; bf16x2_t b = __builtin_convertvector(v, bf16x2_t); return __builtin_bit_cast(unsigned, b); }
; __device__ __forceinline__ float bflo(unsigned w) { return __uint_as_float(w << 16); }
; __device__ __forceinline__ float bfhi(unsigned w) { return __uint_as_float(w & 0xffff0000u); }
; #define MFMA32(a, b, c) __builtin_amdgcn_mfma_f32_32x32x16_bf16((a), (b), (c), 0, 0, 0)
; __device__ __forceinline__ void mlstm_unit(const Params& p, int l, int b, int h, LAS unsigned char* lds) {
;     ...
;         {
;             const int dblk = w4 & 1, vblk = w4 >> 1;
; #pragma unroll
;             for (int i = 0; i < 16; ++i) Cacc[i] *= decay;
; #pragma unroll
;             for (int c = 0; c < 4; ++c) { const bf16x8 af = lds_rd16(L + ML_KT + (32 * dblk + r32) * 144 + hi * 16 + c * 32);
;                 const u32x4 vv = *(const LAS u32x4*)(L + ML_VT + (32 * vblk + r32) * 144 + hi * 16 + c * 32);
;                 const f32x4 u0 = *(const LAS f32x4*)(L + ML_TAB + T_U + (16 * c + 8 * hi) * 4), u1 = *(const LAS f32x4*)(L + ML_TAB + T_U + (16 * c + 8 * hi + 4) * 4);
;                 u32x4 sv; sv.x = pk2(bflo(vv.x) * u0[0], bfhi(vv.x) * u0[1]); sv.y = pk2(bflo(vv.y) * u0[2], bfhi(vv.y) * u0[3]); sv.z = pk2(bflo(vv.z) * u1[0], bfhi(vv.z) * u1[1]); sv.w = pk2(bflo(vv.w) * u1[2], bfhi(vv.w) * u1[3]);
;                 Cacc = MFMA32(af, __builtin_bit_cast(bf16x8, sv), Cacc); }
; #pragma unroll
;             for (int ig = 0; ig < 4; ++ig) { const int d0 = 32 * dblk + 8 * ig + 4 * hi; u32x2 pw; pw.x = pk2(Cacc[4 * ig], Cacc[4 * ig + 1]); pw.y = pk2(Cacc[4 * ig + 2], Cacc[4 * ig + 3]);
;                 *(LAS u32x2*)(CTn + (32 * vblk + r32) * 144 + d0 * 2) = pw; }
;         }
.LBB0_466:
	s_or_b64 exec, exec, s[76:77]
	ds_read_b128 v[18:21], v116 offset:27648
	ds_read_b128 v[22:25], v116 offset:27680
	ds_read_b128 v[26:29], v134 offset:65280
	ds_read_b128 v[34:37], v134 offset:65296
	ds_read_b128 v[162:165], v135 offset:18496
	ds_read_b128 v[166:169], v116 offset:27712
	ds_read_b128 v[170:173], v134 offset:65408
	ds_read_b128 v[174:177], v134 offset:65424
	ds_read_b128 v[178:181], v135 offset:18528
	ds_read_b128 v[182:185], v116 offset:27744
	ds_read_b128 v[186:189], v134 offset:65472
	ds_read_b128 v[190:193], v134 offset:65488
	v_sub_f32_e32 v16, v136, v32
	s_waitcnt lgkmcnt(11)
	v_lshlrev_b32_e32 v30, 16, v18
	v_and_b32_e32 v31, 0xffff0000, v18
	s_waitcnt lgkmcnt(9)
	v_pk_mul_f32 v[26:27], v[26:27], v[30:31]
	v_mul_f32_e32 v16, 0x3fb8aa3b, v16
	v_cvt_pk_bf16_f32 v18, v26, v27
	v_lshlrev_b32_e32 v26, 16, v19
	v_and_b32_e32 v27, 0xffff0000, v19
	v_pk_mul_f32 v[26:27], v[28:29], v[26:27]
	v_exp_f32_e32 v16, v16
	v_cvt_pk_bf16_f32 v19, v26, v27
	v_lshlrev_b32_e32 v26, 16, v20
	v_and_b32_e32 v27, 0xffff0000, v20
	s_waitcnt lgkmcnt(8)
	v_pk_mul_f32 v[26:27], v[34:35], v[26:27]
	v_pk_mul_f32 v[14:15], v[14:15], v[16:17] op_sel_hi:[1,0]
	v_cvt_pk_bf16_f32 v20, v26, v27
	v_lshlrev_b32_e32 v26, 16, v21
	v_and_b32_e32 v27, 0xffff0000, v21
	v_pk_mul_f32 v[26:27], v[36:37], v[26:27]
	v_pk_mul_f32 v[12:13], v[12:13], v[16:17] op_sel_hi:[1,0]
	v_cvt_pk_bf16_f32 v21, v26, v27
	ds_read_b128 v[26:29], v135 offset:18432
	ds_read_b128 v[34:37], v135 offset:18464
	v_pk_mul_f32 v[10:11], v[10:11], v[16:17] op_sel_hi:[1,0]
	v_pk_mul_f32 v[8:9], v[8:9], v[16:17] op_sel_hi:[1,0]
	v_pk_mul_f32 v[6:7], v[6:7], v[16:17] op_sel_hi:[1,0]
	v_pk_mul_f32 v[4:5], v[4:5], v[16:17] op_sel_hi:[1,0]
	v_pk_mul_f32 v[2:3], v[2:3], v[16:17] op_sel_hi:[1,0]
	v_pk_mul_f32 v[0:1], v[0:1], v[16:17] op_sel_hi:[1,0]
	v_lshlrev_b32_e32 v30, 16, v22
	v_and_b32_e32 v31, 0xffff0000, v22
	s_waitcnt lgkmcnt(1)
	v_mfma_f32_32x32x16_bf16 v[0:15], v[26:29], v[18:21], v[0:15]
	ds_read_b128 v[18:21], v134 offset:65344
	ds_read_b128 v[26:29], v134 offset:65360
	v_lshlrev_b32_e32 v22, 16, v23
	v_and_b32_e32 v23, 0xffff0000, v23
	s_cmp_eq_u32 s44, 0
	s_waitcnt lgkmcnt(1)
	v_pk_mul_f32 v[18:19], v[18:19], v[30:31]
	v_pk_mul_f32 v[20:21], v[20:21], v[22:23]
	v_cvt_pk_bf16_f32 v18, v18, v19
	v_cvt_pk_bf16_f32 v19, v20, v21
	v_lshlrev_b32_e32 v20, 16, v24
	v_and_b32_e32 v21, 0xffff0000, v24
	v_lshlrev_b32_e32 v22, 16, v25
	v_and_b32_e32 v23, 0xffff0000, v25
	s_waitcnt lgkmcnt(0)
	v_pk_mul_f32 v[20:21], v[26:27], v[20:21]
	v_pk_mul_f32 v[22:23], v[28:29], v[22:23]
	v_cvt_pk_bf16_f32 v20, v20, v21
	v_cvt_pk_bf16_f32 v21, v22, v23
	s_cselect_b64 s[76:77], -1, 0
	s_and_b64 s[78:79], s[76:77], exec
	v_mfma_f32_32x32x16_bf16 v[0:15], v[34:37], v[18:21], v[0:15]
	s_cselect_b32 s64, 0xd800, s88
	v_add_u32_e32 v17, s64, v118
	v_lshlrev_b32_e32 v30, 16, v166
	v_and_b32_e32 v31, 0xffff0000, v166
	v_pk_mul_f32 v[26:27], v[170:171], v[30:31]
	s_mov_b64 s[78:79], -1
	v_cvt_pk_bf16_f32 v22, v26, v27
	v_lshlrev_b32_e32 v26, 16, v167
	v_and_b32_e32 v27, 0xffff0000, v167
	v_pk_mul_f32 v[26:27], v[172:173], v[26:27]
	s_and_b64 vcc, exec, s[72:73]
	v_cvt_pk_bf16_f32 v23, v26, v27
	v_lshlrev_b32_e32 v26, 16, v168
	v_and_b32_e32 v27, 0xffff0000, v168
	v_pk_mul_f32 v[26:27], v[174:175], v[26:27]
	s_nop 0
	v_cvt_pk_bf16_f32 v24, v26, v27
	v_lshlrev_b32_e32 v26, 16, v169
	v_and_b32_e32 v27, 0xffff0000, v169
	v_pk_mul_f32 v[26:27], v[176:177], v[26:27]
	s_nop 0
	v_cvt_pk_bf16_f32 v25, v26, v27
	s_nop 1
	v_mfma_f32_32x32x16_bf16 v[0:15], v[162:165], v[22:25], v[0:15]
	v_lshlrev_b32_e32 v30, 16, v182
	v_and_b32_e32 v31, 0xffff0000, v182
	v_pk_mul_f32 v[26:27], v[186:187], v[30:31]
	s_nop 0
	v_cvt_pk_bf16_f32 v22, v26, v27
	v_lshlrev_b32_e32 v26, 16, v183
	v_and_b32_e32 v27, 0xffff0000, v183
	v_pk_mul_f32 v[26:27], v[188:189], v[26:27]
	s_nop 0
	v_cvt_pk_bf16_f32 v23, v26, v27
	v_lshlrev_b32_e32 v26, 16, v184
	v_and_b32_e32 v27, 0xffff0000, v184
	v_pk_mul_f32 v[26:27], v[190:191], v[26:27]
	s_nop 0
	v_cvt_pk_bf16_f32 v24, v26, v27
	v_lshlrev_b32_e32 v26, 16, v185
	v_and_b32_e32 v27, 0xffff0000, v185
	v_pk_mul_f32 v[26:27], v[192:193], v[26:27]
	s_nop 0
	v_cvt_pk_bf16_f32 v25, v26, v27
	s_nop 1
	v_mfma_f32_32x32x16_bf16 v[0:15], v[178:181], v[22:25], v[0:15]
	s_nop 11
	v_cvt_pk_bf16_f32 v18, v0, v1
	v_cvt_pk_bf16_f32 v19, v2, v3
	v_cvt_pk_bf16_f32 v20, v4, v5
	v_cvt_pk_bf16_f32 v21, v6, v7
	ds_write2_b64 v17, v[18:19], v[20:21] offset1:2
	v_cvt_pk_bf16_f32 v18, v8, v9
	v_cvt_pk_bf16_f32 v19, v10, v11
	v_cvt_pk_bf16_f32 v20, v12, v13
	v_cvt_pk_bf16_f32 v21, v14, v15
	ds_write2_b64 v17, v[18:19], v[20:21] offset0:4 offset1:6
	s_cbranch_vccz .LBB0_470
	s_andn2_b64 vcc, exec, s[74:75]
	s_cbranch_vccnz .LBB0_469
; #define LAS __attribute__((address_space(3)))
; __device__ __forceinline__ float bflo(unsigned w) { return __uint_as_float(w << 16); }
; __device__ __forceinline__ float bfhi(unsigned w) { return __uint_as_float(w & 0xffff0000u); }
; __device__ __forceinline__ void mlstm_unit(const Params& p, int l, int b, int h, LAS unsigned char* lds) {
;     ...
;         } else if (w4 == 1) {
;             const LAS unsigned char* nv = L + ML_TAB + (cur ? T_NV1 : T_NV0); float s = 0.f;
; #pragma unroll
;             for (int c = 0; c < 8; ++c) { const u32x4 v = *(const LAS u32x4*)(L + ML_QS + lane * 144 + c * 16); const f32x4 n0 = *(const LAS f32x4*)(nv + c * 32), n1 = *(const LAS f32x4*)(nv + c * 32 + 16);
;                 s += bflo(v.x) * n0[0] + bfhi(v.x) * n0[1] + bflo(v.y) * n0[2] + bfhi(v.y) * n0[3] + bflo(v.z) * n1[0] + bfhi(v.z) * n1[1] + bflo(v.w) * n1[2] + bfhi(v.w) * n1[3]; }
;             *(LAS float*)(L + ML_TAB + T_DI + lane * 4) = s;
	s_and_b64 s[78:79], s[76:77], exec
	s_movk_i32 s64, 0x800
	s_cselect_b32 s64, s64, 0x900
	s_add_i32 s64, s85, s64
	v_add_u32_e32 v17, s85, v119
	v_mov_b32_e32 v85, s64
	ds_read_b128 v[18:21], v17
	ds_read_b128 v[22:25], v17 offset:16
	ds_read_b128 v[26:29], v17 offset:32
	ds_read_b128 v[34:37], v17 offset:48
	ds_read_b128 v[38:41], v85 offset:64512
	ds_read_b128 v[42:45], v85 offset:64528
	ds_read_b128 v[106:109], v85 offset:64544
	ds_read_b128 v[136:139], v85 offset:64560
	s_waitcnt lgkmcnt(7)
	v_and_b32_e32 v86, 0xffff0000, v18
	s_waitcnt lgkmcnt(6)
	v_and_b32_e32 v87, 0xffff0000, v22
	v_lshlrev_b32_e32 v31, 16, v22
	s_waitcnt lgkmcnt(1)
	v_mov_b32_e32 v47, v106
	v_mov_b32_e32 v106, v39
	v_lshlrev_b32_e32 v30, 16, v18
	v_mov_b32_e32 v46, v38
	v_pk_mul_f32 v[38:39], v[106:107], v[86:87]
	v_and_b32_e32 v22, 0xffff0000, v19
	v_pk_fma_f32 v[30:31], v[46:47], v[30:31], v[38:39]
	v_lshlrev_b32_e32 v39, 16, v23
	v_lshlrev_b32_e32 v38, 16, v19
	v_mov_b32_e32 v46, v40
	v_mov_b32_e32 v47, v108
	v_pk_fma_f32 v[30:31], v[46:47], v[38:39], v[30:31]
	v_and_b32_e32 v23, 0xffff0000, v23
	v_mov_b32_e32 v108, v41
	v_pk_fma_f32 v[18:19], v[108:109], v[22:23], v[30:31]
	v_lshlrev_b32_e32 v23, 16, v24
	v_lshlrev_b32_e32 v22, 16, v20
	v_mov_b32_e32 v30, v42
	s_waitcnt lgkmcnt(0)
	v_mov_b32_e32 v31, v136
	v_pk_fma_f32 v[18:19], v[30:31], v[22:23], v[18:19]
	v_and_b32_e32 v23, 0xffff0000, v24
	v_and_b32_e32 v22, 0xffff0000, v20
	v_mov_b32_e32 v136, v43
	v_pk_fma_f32 v[18:19], v[136:137], v[22:23], v[18:19]
	v_lshlrev_b32_e32 v23, 16, v25
	v_lshlrev_b32_e32 v22, 16, v21
	v_mov_b32_e32 v30, v44
	v_mov_b32_e32 v31, v138
	v_pk_fma_f32 v[18:19], v[30:31], v[22:23], v[18:19]
	v_and_b32_e32 v23, 0xffff0000, v25
	v_and_b32_e32 v22, 0xffff0000, v21
	v_mov_b32_e32 v138, v45
	v_pk_fma_f32 v[18:19], v[138:139], v[22:23], v[18:19]
	v_and_b32_e32 v87, 0xffff0000, v34
	v_add_f32_e32 v18, 0, v18
	v_add_f32_e32 v106, v18, v19
	ds_read_b128 v[18:21], v85 offset:64576
	ds_read_b128 v[22:25], v85 offset:64592
	ds_read_b128 v[38:41], v85 offset:64608
	ds_read_b128 v[42:45], v85 offset:64624
	v_and_b32_e32 v86, 0xffff0000, v26
	v_lshlrev_b32_e32 v31, 16, v34
	v_lshlrev_b32_e32 v30, 16, v26
	s_waitcnt lgkmcnt(1)
	v_mov_b32_e32 v47, v38
	v_mov_b32_e32 v38, v19
	v_mov_b32_e32 v46, v18
	v_pk_mul_f32 v[18:19], v[38:39], v[86:87]
	v_mov_b32_e32 v38, v20
	v_pk_fma_f32 v[18:19], v[46:47], v[30:31], v[18:19]
	v_lshlrev_b32_e32 v31, 16, v35
	v_lshlrev_b32_e32 v30, 16, v27
	v_mov_b32_e32 v39, v40
	v_pk_fma_f32 v[18:19], v[38:39], v[30:31], v[18:19]
	v_and_b32_e32 v31, 0xffff0000, v35
	v_and_b32_e32 v30, 0xffff0000, v27
	v_mov_b32_e32 v40, v21
	v_pk_fma_f32 v[18:19], v[40:41], v[30:31], v[18:19]
	v_lshlrev_b32_e32 v21, 16, v36
	v_lshlrev_b32_e32 v20, 16, v28
	v_mov_b32_e32 v26, v22
	s_waitcnt lgkmcnt(0)
	v_mov_b32_e32 v27, v42
	v_pk_fma_f32 v[18:19], v[26:27], v[20:21], v[18:19]
	v_and_b32_e32 v21, 0xffff0000, v36
	v_and_b32_e32 v20, 0xffff0000, v28
	v_mov_b32_e32 v42, v23
	v_pk_fma_f32 v[18:19], v[42:43], v[20:21], v[18:19]
	v_lshlrev_b32_e32 v21, 16, v37
	v_lshlrev_b32_e32 v20, 16, v29
	v_mov_b32_e32 v22, v24
	v_mov_b32_e32 v23, v44
	v_pk_fma_f32 v[18:19], v[22:23], v[20:21], v[18:19]
	v_and_b32_e32 v21, 0xffff0000, v37
	v_and_b32_e32 v20, 0xffff0000, v29
	v_mov_b32_e32 v44, v25
	v_pk_fma_f32 v[18:19], v[44:45], v[20:21], v[18:19]
	s_nop 0
	v_add_f32_e32 v18, v106, v18
	v_add_f32_e32 v106, v18, v19
	ds_read_b128 v[18:21], v17 offset:64
	ds_read_b128 v[22:25], v17 offset:80
	ds_read_b128 v[26:29], v85 offset:64640
	ds_read_b128 v[34:37], v85 offset:64656
	ds_read_b128 v[38:41], v85 offset:64672
	ds_read_b128 v[42:45], v85 offset:64688
	s_waitcnt lgkmcnt(4)
	v_and_b32_e32 v87, 0xffff0000, v22
	v_and_b32_e32 v86, 0xffff0000, v18
	v_lshlrev_b32_e32 v31, 16, v22
	s_waitcnt lgkmcnt(1)
	v_mov_b32_e32 v47, v38
	v_mov_b32_e32 v38, v27
	v_lshlrev_b32_e32 v30, 16, v18
	v_mov_b32_e32 v46, v26
	v_pk_mul_f32 v[26:27], v[38:39], v[86:87]
	v_mov_b32_e32 v38, v28
	v_pk_fma_f32 v[26:27], v[46:47], v[30:31], v[26:27]
	v_lshlrev_b32_e32 v31, 16, v23
	v_lshlrev_b32_e32 v30, 16, v19
	v_mov_b32_e32 v39, v40
	v_pk_fma_f32 v[26:27], v[38:39], v[30:31], v[26:27]
	v_and_b32_e32 v23, 0xffff0000, v23
	v_and_b32_e32 v22, 0xffff0000, v19
	v_mov_b32_e32 v40, v29
	v_pk_fma_f32 v[18:19], v[40:41], v[22:23], v[26:27]
	v_lshlrev_b32_e32 v23, 16, v24
	v_lshlrev_b32_e32 v22, 16, v20
	v_mov_b32_e32 v26, v34
	s_waitcnt lgkmcnt(0)
	v_mov_b32_e32 v27, v42
	v_pk_fma_f32 v[18:19], v[26:27], v[22:23], v[18:19]
	v_and_b32_e32 v23, 0xffff0000, v24
	v_and_b32_e32 v22, 0xffff0000, v20
	v_mov_b32_e32 v42, v35
	v_pk_fma_f32 v[18:19], v[42:43], v[22:23], v[18:19]
	v_lshlrev_b32_e32 v23, 16, v25
	v_lshlrev_b32_e32 v22, 16, v21
	v_mov_b32_e32 v26, v36
	v_mov_b32_e32 v27, v44
	v_pk_fma_f32 v[18:19], v[26:27], v[22:23], v[18:19]
	v_and_b32_e32 v23, 0xffff0000, v25
	v_and_b32_e32 v22, 0xffff0000, v21
	v_mov_b32_e32 v44, v37
	v_pk_fma_f32 v[18:19], v[44:45], v[22:23], v[18:19]
	s_nop 0
	v_add_f32_e32 v18, v106, v18
	v_add_f32_e32 v106, v18, v19
	ds_read_b128 v[18:21], v17 offset:96
	ds_read_b128 v[22:25], v17 offset:112
	ds_read_b128 v[26:29], v85 offset:64704
	ds_read_b128 v[34:37], v85 offset:64720
	ds_read_b128 v[38:41], v85 offset:64736
	ds_read_b128 v[42:45], v85 offset:64752
	s_waitcnt lgkmcnt(4)
	v_and_b32_e32 v87, 0xffff0000, v22
	v_and_b32_e32 v86, 0xffff0000, v18
	v_lshlrev_b32_e32 v31, 16, v22
	s_waitcnt lgkmcnt(1)
	v_mov_b32_e32 v47, v38
	v_mov_b32_e32 v38, v27
	v_lshlrev_b32_e32 v30, 16, v18
	v_mov_b32_e32 v46, v26
	v_pk_mul_f32 v[26:27], v[38:39], v[86:87]
	v_mov_b32_e32 v38, v28
	v_pk_fma_f32 v[26:27], v[46:47], v[30:31], v[26:27]
	v_lshlrev_b32_e32 v31, 16, v23
	v_lshlrev_b32_e32 v30, 16, v19
	v_mov_b32_e32 v39, v40
	v_pk_fma_f32 v[26:27], v[38:39], v[30:31], v[26:27]
	v_and_b32_e32 v23, 0xffff0000, v23
	v_and_b32_e32 v22, 0xffff0000, v19
	v_mov_b32_e32 v40, v29
	v_pk_fma_f32 v[18:19], v[40:41], v[22:23], v[26:27]
	v_lshlrev_b32_e32 v23, 16, v24
	v_lshlrev_b32_e32 v22, 16, v20
	v_mov_b32_e32 v26, v34
	s_waitcnt lgkmcnt(0)
	v_mov_b32_e32 v27, v42
	v_pk_fma_f32 v[18:19], v[26:27], v[22:23], v[18:19]
	v_and_b32_e32 v23, 0xffff0000, v24
	v_and_b32_e32 v22, 0xffff0000, v20
	v_mov_b32_e32 v42, v35
	v_pk_fma_f32 v[18:19], v[42:43], v[22:23], v[18:19]
	v_lshlrev_b32_e32 v23, 16, v25
	v_lshlrev_b32_e32 v22, 16, v21
	v_mov_b32_e32 v26, v36
	v_mov_b32_e32 v27, v44
	v_pk_fma_f32 v[18:19], v[26:27], v[22:23], v[18:19]
	v_and_b32_e32 v23, 0xffff0000, v25
	v_and_b32_e32 v22, 0xffff0000, v21
	v_mov_b32_e32 v44, v37
	v_pk_fma_f32 v[18:19], v[44:45], v[22:23], v[18:19]
	s_nop 0
	v_add_f32_e32 v17, v106, v18
	v_add_f32_e32 v17, v17, v19
	v_add_u32_e32 v18, s67, v120
	ds_write_b32 v18, v17
